# v109 + E2/F reuse the expert prefix E1 left in LDS (no reload, no prefix recompute)
# baseline (speedup 1.0000x reference)
; __device__ __forceinline__ void moe_prefix(const Params& p, int* s_off, int* s_rb) {
;   __syncthreads();
;   int* s_cnt = (int*)((char*)s_off - 2 * GEMM_SMEM);
;   if (threadIdx.x < NEXP) s_cnt[threadIdx.x] = p.cnt[threadIdx.x];
;   __syncthreads();
;   if (threadIdx.x == 0) {
;     int o = 0, r = 0;
;     for (int e = 0; e < NEXP; e++) {
;       s_off[e] = o; s_rb[e] = r;
;       const int c = s_cnt[e];
;       o += c; r += (c + 127) >> 7;
;     }
;     s_off[NEXP] = o; s_rb[NEXP] = r;
;   }
;   __syncthreads();
.Lxb9_done:
.LBB0_1342:
	s_or_b64 exec, exec, s[0:1]
	s_waitcnt lgkmcnt(0)
	s_barrier
	s_barrier
	s_branch .Lmp_e2
	s_and_saveexec_b64 s[0:1], s[52:53]
	s_cbranch_execz .LBB0_1344
	v_lshrrev_b32_e32 v0, 2, v149
	v_mul_u32_u24_e32 v0, 0x20100, v0
	global_load_dword v0, v0, s[62:63]
	s_waitcnt vmcnt(0)
	ds_write_b32 v131, v0

; __device__ void phaseE2(const Params& p, char* smem) {
;   int* s_off = (int*)(smem + 2 * GEMM_SMEM);
;   int* s_rb = s_off + 72;
;   moe_prefix(p, s_off, s_rb);
;   xcd_queue_run(p.bar + QW_BASE + 1536, s_rb[NEXP], smem + 2 * GEMM_SMEM + 800, [&](int j, int q) {
;     const int rbg = q, nt = j;
;     int e = 0;
;     while (s_rb[e + 1] <= rbg) e++;
;     const int rb = rbg - s_rb[e];
;     const int cnt = p.cnt[e];
;     const int rows = min(128, cnt - rb * 128);
;     const int slot0 = s_off[e] + rb * 128;
;     const int n0 = nt * 128;
;     const float* wd = p.w_down + (size_t)e * DEXP * DM;
;     const float* lg = p.list_gate + e * CAP + rb * 128;
;     auto rowf = [&](int r) { int rr = r < rows ? r : 0; return (const void*)(p.H + (size_t)(slot0 + rr) * DEXP); };
;     auto colf = [&](int c) { return (const void*)(wd + n0 + c); };
.Lmp_e2:
	s_mov_b64 s[0:1], src_shared_base
	s_add_u32 s0, s82, 0x4e00
	s_addc_u32 s22, s83, 0
	s_add_i32 s2, 0, 0x10220
	v_mov_b32_e32 v0, s2
	s_waitcnt lgkmcnt(0)
	s_barrier
	ds_read_b32 v108, v0
	v_and_b32_e32 v0, 0x7f, v128
	v_lshlrev_b32_e32 v1, 5, v170
	v_lshlrev_b32_e32 v2, 6, v0
	v_and_b32_e32 v3, 56, v127
	v_xad_u32 v109, v1, v3, v2
	v_lshlrev_b32_e32 v1, 2, v170
	v_readlane_b32 s4, v240, 26
	v_bitop3_b32 v3, v1, v171, 1 bitop3:0x36
	v_readlane_b32 s12, v240, 34
	v_readlane_b32 s13, v240, 35
	v_readlane_b32 s14, v240, 36
	v_readlane_b32 s15, v240, 37
	v_readlane_b32 s16, v240, 38
	v_readlane_b32 s17, v240, 39
	v_lshl_add_u32 v110, v3, 3, v2
	v_bitop3_b32 v3, v1, v171, 2 bitop3:0x36
	v_bitop3_b32 v1, v1, v171, 3 bitop3:0x36
	s_waitcnt vmcnt(0)
	v_mov_b32_e32 v81, 0
	v_lshlrev_b32_e32 v80, 2, v0
	v_readlane_b32 s18, v240, 40
	v_readlane_b32 s19, v240, 41
	s_mov_b64 s[12:13], s[16:17]
	v_lshl_add_u32 v111, v3, 3, v2
	v_lshl_add_u32 v112, v1, 3, v2
	v_lshl_add_u64 v[0:1], s[12:13], 0, v[80:81]
	v_lshlrev_b32_e32 v2, 17, v170
	v_mov_b32_e32 v3, v81
	v_lshl_add_u64 v[82:83], v[0:1], 0, v[2:3]
	v_lshlrev_b32_e32 v0, 1, v130
	v_mov_b32_e32 v1, v81
	v_lshl_add_u64 v[84:85], s[60:61], 0, v[0:1]
	v_lshlrev_b32_e32 v0, 10, v128
	s_mov_b32 s2, 0xe0000
	v_readlane_b32 s5, v240, 27
	v_readlane_b32 s8, v240, 30
	v_and_or_b32 v80, v0, s2, v80
	s_getreg_b32 s23, hwreg(HW_REG_XCC_ID, 0, 4)
	v_readlane_b32 s6, v240, 28
	v_readlane_b32 s7, v240, 29
	v_readlane_b32 s9, v240, 31
	v_readlane_b32 s10, v240, 32
	v_readlane_b32 s11, v240, 33
	v_lshl_add_u64 v[0:1], s[12:13], 0, v[80:81]
	s_mov_b64 s[4:5], 0x40000
	s_add_u32 s8, s58, 0x80
	s_mov_b32 s3, 0
	v_lshl_add_u32 v113, v109, 1, 0
	v_lshl_add_u32 v114, v110, 1, 0
	v_lshl_add_u32 v115, v111, 1, 0
	v_lshl_add_u32 v116, v112, 1, 0
	v_lshl_add_u64 v[86:87], s[58:59], 0, v[124:125]
	v_lshl_add_u64 v[88:89], v[0:1], 0, s[4:5]
	s_mov_b64 s[6:7], 0x80
	s_addc_u32 s9, s59, 0
	s_add_i32 s24, 0, 0x10124
	s_mov_b64 s[10:11], 0x200000
	s_mov_b32 s25, 0x10000
	s_movk_i32 s26, 0x2000
	s_movk_i32 s27, 0x4000
	s_movk_i32 s28, 0x6000
	s_mov_b32 s29, 0x8000
	s_mov_b32 s30, 0xa000
	s_mov_b32 s31, 0xc000
	s_mov_b32 s36, 0xe000
	s_mov_b32 s37, 0x12000
	s_mov_b32 s38, 0x14000
	s_mov_b32 s39, 0x16000
	s_mov_b32 s40, 0x18000
	s_mov_b32 s41, 0x1a000
	s_mov_b32 s42, 0x1c000
	s_mov_b32 s43, 0x1e000
	s_mov_b32 s44, 0x1f000
	s_mov_b32 s45, s23
	s_mov_b32 s46, 0
	s_mov_b64 s[14:15], s[18:19]
	s_branch .LBB0_1348

; __device__ __forceinline__ float bflo(unsigned v) { return __uint_as_float(v << 16); }
; __device__ __forceinline__ float bfhi(unsigned v) { return __uint_as_float(v & 0xffff0000u); }
; __device__ void phaseF(const Params& p, char* smem) {
;     ...
;   const int tid = threadIdx.x, lane = tid & 63, w = tid >> 6;
;   for (int rp = blockIdx.x * 4 + w; rp < NTOK / 2; rp += gridDim.x * 4) {
;     int sl[2][2];
; #pragma unroll
;     for (int h = 0; h < 2; h++) {
;       const int row = rp * 2 + h;
;       const int2 te = *(const int2*)&p.tok_e[row * 2], tp = *(const int2*)&p.tok_pos[row * 2];
;       sl[h][0] = s_off[te.x] + tp.x;
;       sl[h][1] = s_off[te.y] + tp.y;
;     }
;     float4 v[2][4];
; #pragma unroll
;     for (int h = 0; h < 2; h++) {
;       const int row = rp * 2 + h;
; #pragma unroll
;       for (int i = 0; i < 4; i++) {
;         const int c = lane * 4 + 256 * i;
;         const uint2 xb2 = *(const uint2*)&p.X1B[(size_t)row * DM + c];
;         const float4 xv = make_float4(bflo(xb2.x), bfhi(xb2.x), bflo(xb2.y), bfhi(xb2.y));
;         const uint2 ya = *(const uint2*)&p.Y[(size_t)sl[h][0] * DM + c];
;         const uint2 yb = *(const uint2*)&p.Y[(size_t)sl[h][1] * DM + c];
;         v[h][i].x = ALPHA * xv.x + (bflo(ya.x) + bflo(yb.x));
;         v[h][i].y = ALPHA * xv.y + (bfhi(ya.x) + bfhi(yb.x));
;         v[h][i].z = ALPHA * xv.z + (bflo(ya.y) + bflo(yb.y));
;         v[h][i].w = ALPHA * xv.w + (bfhi(ya.y) + bfhi(yb.y));
;       }
;     }
.Lmp_f:
	v_readlane_b32 s2, v240, 42
	s_movk_i32 s0, 0x2000
	s_waitcnt lgkmcnt(0)
	v_lshl_add_u32 v23, s2, 2, v129
	v_cmp_gt_i32_e32 vcc, s0, v23
	s_barrier
	v_readlane_b32 s3, v240, 43
	s_and_saveexec_b64 s[0:1], vcc
	s_cbranch_execz .LBB0_1431
	v_and_b32_e32 v2, 0xfc, v127
	v_readlane_b32 s4, v240, 26
	v_readlane_b32 s0, v240, 1
	v_lshlrev_b32_e32 v0, 2, v2
	v_mov_b32_e32 v1, 0
	v_readlane_b32 s18, v240, 40
	v_readlane_b32 s19, v240, 41
	v_readlane_b32 s1, v240, 2
	v_readlane_b32 s5, v240, 27
	v_readlane_b32 s6, v240, 28
	v_readlane_b32 s7, v240, 29
	v_readlane_b32 s8, v240, 30
	v_readlane_b32 s9, v240, 31
	v_lshl_add_u64 v[8:9], s[18:19], 0, v[0:1]
	v_lshl_add_u64 v[10:11], s[84:85], 0, v[0:1]
	global_load_dwordx4 v[194:197], v[8:9], off
	global_load_dwordx4 v[198:201], v[8:9], off offset:1024
	global_load_dwordx4 v[202:205], v[8:9], off offset:2048
	global_load_dwordx4 v[206:209], v[8:9], off offset:3072
	global_load_dwordx4 v[210:213], v[10:11], off
	global_load_dwordx4 v[214:217], v[10:11], off offset:1024
	global_load_dwordx4 v[218:221], v[10:11], off offset:2048
	global_load_dwordx4 v[222:225], v[10:11], off offset:3072
	v_lshlrev_b32_e32 v2, 1, v2
	v_mov_b32_e32 v3, v1
	v_lshl_add_u64 v[16:17], s[86:87], 0, v[0:1]
	v_lshlrev_b32_e32 v0, 1, v129
	s_lshl_b32 s3, s0, 2
	v_lshl_add_u64 v[12:13], s[56:57], 0, v[2:3]
	v_lshl_add_u64 v[14:15], s[60:61], 0, v[2:3]
	v_lshl_add_u32 v18, s2, 3, v0
	s_lshl_b32 s5, s0, 3
	v_lshl_add_u32 v20, s2, 4, v148
	s_lshl_b32 s6, s0, 4
	s_mov_b64 s[0:1], 0
	s_add_i32 s7, 0, 0x10000
	s_mov_b32 s2, 0x3f9837f0
	s_mov_b32 s4, 0x3a800000
	v_mov_b32_e32 v22, 0x3727c5ac
	s_mov_b32 s8, 0x800000
	s_movk_i32 s9, 0x1fff
	v_readlane_b32 s10, v240, 32
	v_readlane_b32 s11, v240, 33
	v_readlane_b32 s12, v240, 34
	v_readlane_b32 s13, v240, 35
	v_readlane_b32 s14, v240, 36
	v_readlane_b32 s15, v240, 37
	v_readlane_b32 s16, v240, 38
	v_readlane_b32 s17, v240, 39
	s_waitcnt vmcnt(0)
	.p2align 6
